# baseline (speedup 1.0000x reference)
; __device__ void attn_item(const u16* __restrict__ q, const u16* __restrict__ k, const u16* __restrict__ vt,
;                           u16* __restrict__ mix, int bh, int qt, int tid) {
;   const int lane = tid & 63, n = lane & 31, hf = lane >> 5;
;   const int t0 = qt * 32;
;   const u16* qb = q + (size_t)bh * SEQ * 64;
;   const u16* kbp = k + (size_t)bh * SEQ * 64;
;   const u16* vb = vt + (size_t)bh * 64 * SEQ;
;   bf16x8 qf[4];
; #pragma unroll
;   for (int kk = 0; kk < 4; ++kk) qf[kk] = *(const bf16x8*)(qb + (size_t)(t0 + n) * 64 + kk * 16 + hf * 8);
;   const int krow = (n & ~0xC) | ((n & 4) << 1) | ((n & 8) >> 1);
;   f32x16 o0 = {}, o1 = {};
;   float carry = 1.f;
;   bf16x8 kfn[4], vfn[2][2];
; #pragma unroll
;   for (int kk = 0; kk < 4; ++kk) kfn[kk] = *(const bf16x8*)(kbp + (size_t)(t0 + krow) * 64 + kk * 16 + hf * 8);
; #pragma unroll
;   for (int mt = 0; mt < 2; ++mt)
; #pragma unroll
;     for (int c = 0; c < 2; ++c) vfn[mt][c] = *(const bf16x8*)(vb + (size_t)(mt * 32 + n) * SEQ + t0 + c * 16 + hf * 8);
;   for (int kb = t0; kb >= 0; kb -= 32) {
;     bf16x8 kf[4], vf[2][2];
; #pragma unroll
;     for (int kk = 0; kk < 4; ++kk) kf[kk] = kfn[kk];
; #pragma unroll
;     for (int mt = 0; mt < 2; ++mt)
; #pragma unroll
;       for (int c = 0; c < 2; ++c) vf[mt][c] = vfn[mt][c];
;     if (kb >= 32) {
;       const int kn = kb - 32;
; #pragma unroll
;       for (int kk = 0; kk < 4; ++kk) kfn[kk] = *(const bf16x8*)(kbp + (size_t)(kn + krow) * 64 + kk * 16 + hf * 8);
; #pragma unroll
;       for (int mt = 0; mt < 2; ++mt)
; #pragma unroll
;         for (int c = 0; c < 2; ++c) vfn[mt][c] = *(const bf16x8*)(vb + (size_t)(mt * 32 + n) * SEQ + kn + c * 16 + hf * 8);
;     }
;     f32x16 s = {};
; #pragma unroll
;     for (int kk = 0; kk < 4; ++kk) s = __builtin_amdgcn_mfma_f32_32x32x16_bf16(kf[kk], qf[kk], s, 0, 0, 0);
;     float w[16], be[16];
;     const bool diag = (kb == t0);
; #pragma unroll
;     for (int r = 0; r < 16; ++r) {
;       float e = __builtin_amdgcn_exp2f(s[r]);
;       float ww = __builtin_amdgcn_rcpf(1.f + e);
; __device__ void attn_phase(const u16* q, const u16* k, const u16* vt, u16* mix, int tid) {
;   const int wv = tid >> 6;
;   const int gw = blockIdx.x * 8 + wv, nw = gridDim.x * 8;
;   for (int it = gw; it < 64 * 128; it += nw) {
;     int bh = it >> 7, qt = it & 127;
;     attn_item(q, k, vt, mix, bh, qt, tid);
.LBB0_70:
	s_and_b64 vcc, exec, s[0:1]
	s_cbranch_vccz .LBB0_212
	s_cmp_gt_i32 s77, 1
	s_mov_b64 s[0:1], -1
	s_cbranch_scc0 .LBB0_210
	s_cmp_gt_i32 s77, 2
	s_cbranch_scc0 .LBB0_190
	s_add_u32 s0, s79, 0x10000000
	s_addc_u32 s1, s76, 0
	s_add_u32 s72, s79, 0x12000000
	v_writelane_b32 v226, s0, 16
	s_addc_u32 s73, s76, 0
	s_nop 0
	v_writelane_b32 v226, s1, 17
	s_add_u32 s0, s79, 0x14000000
	s_addc_u32 s1, s76, 0
	v_writelane_b32 v226, s0, 18
	s_cmp_gt_i32 s77, 3
	s_nop 0
	v_writelane_b32 v226, s1, 19
	s_mov_b64 s[0:1], -1
	s_cbranch_scc0 .LBB0_101
	v_readfirstlane_b32 s0, v164
	s_lshr_b32 s0, s0, 8
	s_cmp_eq_u32 s0, 1
	s_cbranch_scc0 .Lstag_attn
	s_sleep 9
.Lstag_attn:
	v_writelane_b32 v226, s92, 20
	v_ashrrev_i32_e32 v0, 6, v164
	v_add_u32_e32 v143, s22, v0
	v_writelane_b32 v226, s93, 21
	v_writelane_b32 v226, s18, 22
	v_bfe_u32 v0, v164, 5, 1
	s_mov_b64 s[92:93], s[88:89]
	v_writelane_b32 v226, s19, 23
	v_writelane_b32 v226, s83, 24
	v_writelane_b32 v226, s82, 25
	v_writelane_b32 v226, s67, 26
	v_writelane_b32 v226, s66, 27
	v_writelane_b32 v226, s43, 28
	v_writelane_b32 v226, s42, 29
	v_writelane_b32 v226, s36, 30
	s_mov_b32 s70, s31
	s_movk_i32 s0, 0x2000
	v_writelane_b32 v226, s37, 31
	v_writelane_b32 v226, s34, 32
	v_and_b32_e32 v140, 31, v164
	v_lshlrev_b32_e32 v142, 3, v0
	v_lshlrev_b32_e32 v141, 2, v0
	v_writelane_b32 v226, s35, 33
	v_cmp_gt_i32_e32 vcc, s0, v143
	s_mov_b64 s[0:1], exec
	s_mov_b64 s[82:83], s[0:1]
	s_and_b64 s[0:1], s[0:1], vcc
	s_mov_b64 exec, s[0:1]
	s_cbranch_execz .LBB0_85
	v_cmp_eq_u32_e32 vcc, 0, v0
	v_or_b32_e32 v0, 1, v142
	v_cmp_lt_u32_e64 s[6:7], v0, v140
	v_or_b32_e32 v0, 2, v142
	v_cmp_lt_u32_e64 s[8:9], v0, v140
	v_or_b32_e32 v0, 3, v142
	v_cmp_lt_u32_e64 s[10:11], v0, v140
	v_or_b32_e32 v0, 4, v142
	v_cmp_lt_u32_e64 s[12:13], v0, v140
	v_or_b32_e32 v0, 5, v142
	v_cmp_lt_u32_e64 s[14:15], v0, v140
	v_or_b32_e32 v0, 6, v142
	v_cmp_lt_u32_e64 s[16:17], v0, v140
	v_or_b32_e32 v0, 7, v142
	v_cmp_lt_u32_e64 s[18:19], v0, v140
	v_or_b32_e32 v0, 16, v142
	v_cmp_lt_u32_e64 s[20:21], v0, v140
	v_or_b32_e32 v0, 17, v142
	v_cmp_lt_u32_e64 s[22:23], v0, v140
	v_or_b32_e32 v0, 18, v142
	v_cmp_lt_u32_e64 s[24:25], v0, v140
	v_or_b32_e32 v0, 19, v142
	v_cmp_lt_u32_e64 s[26:27], v0, v140
	v_or_b32_e32 v0, 20, v142
	v_lshlrev_b32_e32 v2, 1, v164
	v_lshrrev_b32_e32 v3, 1, v164
	v_cmp_lt_u32_e64 s[28:29], v0, v140
	v_or_b32_e32 v0, 21, v142
	v_and_b32_e32 v1, 19, v164
	v_and_b32_e32 v2, 8, v2
	v_and_b32_e32 v3, 4, v3
	v_cmp_lt_u32_e64 s[30:31], v0, v140
	v_or_b32_e32 v0, 22, v142
	v_or3_b32 v144, v2, v1, v3
	v_lshlrev_b32_e32 v2, 12, v140
	v_cmp_lt_u32_e64 s[34:35], v0, v140
	v_or_b32_e32 v0, 23, v142
	v_cmp_lt_i32_e64 s[0:1], v155, v154
	v_or_b32_e32 v4, 0x20000, v2
	v_cmp_lt_u32_e64 s[36:37], v0, v140
	v_lshrrev_b32_e32 v0, 6, v164
	v_cndmask_b32_e64 v1, v153, v155, s[0:1]
	v_readlane_b32 s0, v226, 11
	v_cmp_lt_u32_e64 s[4:5], v142, v140
	v_lshlrev_b32_e32 v145, 2, v1
	v_add_u16_e32 v146, s0, v0
	s_mov_b64 s[94:95], 0
	v_lshlrev_b32_e32 v124, 1, v2
	v_lshlrev_b32_e32 v126, 1, v4
	s_branch .LBB0_78
